# grid barrier: last-arriving workgroup of each XCD (returned arrival count) does the L2 write-back + top add; no rank-0 polling stage
# speedup vs baseline: 1.0027x; 1.0027x over previous
; __device__ __forceinline__ unsigned xb_ld(unsigned* p)              { return __hip_atomic_load(p, __ATOMIC_RELAXED, __HIP_MEMORY_SCOPE_AGENT); }
; #define XB_SPIN(cond, bar) do { unsigned _sp = 0; while (cond) { __builtin_amdgcn_s_sleep(1); \
;     if ((++_sp & 255u) == 0u) { if (xb_ld(&(bar)[XB_TMO])) break; if (_sp > XB_SPIN_CAP) { atomicAdd(&(bar)[XB_TMO], 1u); break; } } } } while (0)
; __device__ __forceinline__ void xcd_barrier(const XcdBarrier& b) {
;     ...
;     if (threadIdx.x == 0) {
;         unsigned* bar = b.bar;
;         __builtin_amdgcn_s_waitcnt(0);
;         unsigned nloc = b.st[0], nx = b.st[1];
;         if (nloc == 0u) { xcd_barrier_complete(bar, b.x, nloc, nx); b.st[0] = nloc; b.st[1] = nx; }
;         const unsigned k1 = b.st[2] + 1u, rank = b.st[3]; b.st[2] = k1;
;         (void)__hip_atomic_fetch_add(&bar[XB_XSUB(b.x)], 1u, __ATOMIC_RELAXED, __HIP_MEMORY_SCOPE_AGENT);
;         if (rank == 0u) {
;             XB_SPIN(xb_ld(&bar[XB_XSUB(b.x)]) < k1 * nloc, bar);
;             __builtin_amdgcn_fence(__ATOMIC_RELEASE, "agent");
;             asm volatile("s_waitcnt vmcnt(0)" ::: "memory");
;             (void)__hip_atomic_fetch_add(&bar[XB_TOP], 1u, __ATOMIC_RELAXED, __HIP_MEMORY_SCOPE_AGENT);
;         }
;         XB_SPIN(xb_ld(&bar[XB_TOP]) < k1 * nx, bar);
;         __builtin_amdgcn_fence(__ATOMIC_ACQUIRE, "agent");
;         asm volatile("s_waitcnt vmcnt(0)" ::: "memory");
;     }
.LBB0_235:
	v_mov_b32_e32 v6, s93
	ds_read_b32 v3, v6 offset:8
	v_readlane_b32 s12, v253, 40
	s_lshl_b32 s12, s12, 2
	s_add_u32 s12, s10, s12
	ds_read_b32 v8, v6 offset:12
	s_waitcnt lgkmcnt(0)
	v_add_u32_e32 v3, 1, v3
	s_addc_u32 s13, s11, 0
	ds_write_b32 v6, v3 offset:8
	v_mov_b32_e32 v6, s12
	v_add_co_u32_e32 v6, vcc, 0x1000, v6
	v_mov_b32_e32 v7, s13
	s_nop 0
	v_addc_co_u32_e32 v7, vcc, 0, v7, vcc
	flat_atomic_add v8, v[6:7], v252 offset:1024 sc0
	s_add_u32 s14, s12, 0x1400
	s_addc_u32 s15, s13, 0
	v_mul_lo_u32 v4, v3, v4
	s_waitcnt vmcnt(0) lgkmcnt(0)
	buffer_inv sc1
	v_add_u32_e32 v8, 1, v8
	v_cmp_ne_u32_e32 vcc, v8, v4
	s_cbranch_vccnz .LBB0_248
.Lmy_last_0:
	v_mov_b32_e32 v4, s10
	v_add_co_u32_e32 v6, vcc, 0x3000, v4
	v_mov_b32_e32 v4, s11
	buffer_wbl2 sc1
	s_waitcnt vmcnt(0) lgkmcnt(0)
	s_waitcnt vmcnt(0)
	v_addc_co_u32_e32 v7, vcc, 0, v4, vcc
	flat_atomic_add v[6:7], v232 offset:1024

; __device__ __forceinline__ unsigned xb_ld(unsigned* p)              { return __hip_atomic_load(p, __ATOMIC_RELAXED, __HIP_MEMORY_SCOPE_AGENT); }
; #define XB_SPIN(cond, bar) do { unsigned _sp = 0; while (cond) { __builtin_amdgcn_s_sleep(1); \
;     if ((++_sp & 255u) == 0u) { if (xb_ld(&(bar)[XB_TMO])) break; if (_sp > XB_SPIN_CAP) { atomicAdd(&(bar)[XB_TMO], 1u); break; } } } } while (0)
; __device__ __forceinline__ void xcd_barrier(const XcdBarrier& b) {
;     ...
;     if (threadIdx.x == 0) {
;         unsigned* bar = b.bar;
;         __builtin_amdgcn_s_waitcnt(0);
;         unsigned nloc = b.st[0], nx = b.st[1];
;         if (nloc == 0u) { xcd_barrier_complete(bar, b.x, nloc, nx); b.st[0] = nloc; b.st[1] = nx; }
;         const unsigned k1 = b.st[2] + 1u, rank = b.st[3]; b.st[2] = k1;
;         (void)__hip_atomic_fetch_add(&bar[XB_XSUB(b.x)], 1u, __ATOMIC_RELAXED, __HIP_MEMORY_SCOPE_AGENT);
;         if (rank == 0u) {
;             XB_SPIN(xb_ld(&bar[XB_XSUB(b.x)]) < k1 * nloc, bar);
;             __builtin_amdgcn_fence(__ATOMIC_RELEASE, "agent");
;             asm volatile("s_waitcnt vmcnt(0)" ::: "memory");
;             (void)__hip_atomic_fetch_add(&bar[XB_TOP], 1u, __ATOMIC_RELAXED, __HIP_MEMORY_SCOPE_AGENT);
;         }
;         XB_SPIN(xb_ld(&bar[XB_TOP]) < k1 * nx, bar);
;         __builtin_amdgcn_fence(__ATOMIC_ACQUIRE, "agent");
;         asm volatile("s_waitcnt vmcnt(0)" ::: "memory");
;     }
.LBB0_472:
	v_mov_b32_e32 v6, s93
	ds_read_b32 v3, v6 offset:8
	v_readlane_b32 s10, v253, 40
	s_lshl_b32 s10, s10, 2
	s_add_u32 s10, s8, s10
	ds_read_b32 v8, v6 offset:12
	s_waitcnt lgkmcnt(0)
	v_add_u32_e32 v3, 1, v3
	s_addc_u32 s11, s9, 0
	ds_write_b32 v6, v3 offset:8
	v_mov_b32_e32 v6, s10
	v_add_co_u32_e32 v6, vcc, 0x1000, v6
	v_mov_b32_e32 v7, s11
	s_nop 0
	v_addc_co_u32_e32 v7, vcc, 0, v7, vcc
	flat_atomic_add v8, v[6:7], v252 offset:1024 sc0
	s_add_u32 s12, s10, 0x1400
	s_addc_u32 s13, s11, 0
	v_mul_lo_u32 v4, v3, v4
	s_waitcnt vmcnt(0) lgkmcnt(0)
	buffer_inv sc1
	v_add_u32_e32 v8, 1, v8
	v_cmp_ne_u32_e32 vcc, v8, v4
	s_cbranch_vccnz .LBB0_485
.Lmy_last_1:
	v_mov_b32_e32 v4, s8
	v_add_co_u32_e32 v6, vcc, 0x3000, v4
	v_mov_b32_e32 v4, s9
	buffer_wbl2 sc1
	s_waitcnt vmcnt(0) lgkmcnt(0)
	s_waitcnt vmcnt(0)
	v_addc_co_u32_e32 v7, vcc, 0, v4, vcc
	flat_atomic_add v[6:7], v232 offset:1024

; __device__ __forceinline__ unsigned xb_ld(unsigned* p)              { return __hip_atomic_load(p, __ATOMIC_RELAXED, __HIP_MEMORY_SCOPE_AGENT); }
; #define XB_SPIN(cond, bar) do { unsigned _sp = 0; while (cond) { __builtin_amdgcn_s_sleep(1); \
;     if ((++_sp & 255u) == 0u) { if (xb_ld(&(bar)[XB_TMO])) break; if (_sp > XB_SPIN_CAP) { atomicAdd(&(bar)[XB_TMO], 1u); break; } } } } while (0)
; __device__ __forceinline__ void xcd_barrier(const XcdBarrier& b) {
;     ...
;     if (threadIdx.x == 0) {
;         unsigned* bar = b.bar;
;         __builtin_amdgcn_s_waitcnt(0);
;         unsigned nloc = b.st[0], nx = b.st[1];
;         if (nloc == 0u) { xcd_barrier_complete(bar, b.x, nloc, nx); b.st[0] = nloc; b.st[1] = nx; }
;         const unsigned k1 = b.st[2] + 1u, rank = b.st[3]; b.st[2] = k1;
;         (void)__hip_atomic_fetch_add(&bar[XB_XSUB(b.x)], 1u, __ATOMIC_RELAXED, __HIP_MEMORY_SCOPE_AGENT);
;         if (rank == 0u) {
;             XB_SPIN(xb_ld(&bar[XB_XSUB(b.x)]) < k1 * nloc, bar);
;             __builtin_amdgcn_fence(__ATOMIC_RELEASE, "agent");
;             asm volatile("s_waitcnt vmcnt(0)" ::: "memory");
;             (void)__hip_atomic_fetch_add(&bar[XB_TOP], 1u, __ATOMIC_RELAXED, __HIP_MEMORY_SCOPE_AGENT);
;         }
;         XB_SPIN(xb_ld(&bar[XB_TOP]) < k1 * nx, bar);
;         __builtin_amdgcn_fence(__ATOMIC_ACQUIRE, "agent");
;         asm volatile("s_waitcnt vmcnt(0)" ::: "memory");
;     }
.LBB0_566:
	v_mov_b32_e32 v6, s93
	ds_read_b32 v3, v6 offset:8
	v_readlane_b32 s8, v253, 40
	s_lshl_b32 s8, s8, 2
	s_add_u32 s8, s6, s8
	ds_read_b32 v8, v6 offset:12
	s_waitcnt lgkmcnt(0)
	v_add_u32_e32 v3, 1, v3
	s_addc_u32 s9, s7, 0
	ds_write_b32 v6, v3 offset:8
	v_mov_b32_e32 v6, s8
	v_add_co_u32_e32 v6, vcc, 0x1000, v6
	v_mov_b32_e32 v7, s9
	s_nop 0
	v_addc_co_u32_e32 v7, vcc, 0, v7, vcc
	flat_atomic_add v8, v[6:7], v252 offset:1024 sc0
	s_add_u32 s10, s8, 0x1400
	s_addc_u32 s11, s9, 0
	v_mul_lo_u32 v4, v3, v4
	s_waitcnt vmcnt(0) lgkmcnt(0)
	buffer_inv sc1
	v_add_u32_e32 v8, 1, v8
	v_cmp_ne_u32_e32 vcc, v8, v4
	s_cbranch_vccnz .LBB0_579
.Lmy_last_2:
	v_mov_b32_e32 v4, s6
	v_add_co_u32_e32 v6, vcc, 0x3000, v4
	v_mov_b32_e32 v4, s7
	buffer_wbl2 sc1
	s_waitcnt vmcnt(0) lgkmcnt(0)
	s_waitcnt vmcnt(0)
	v_addc_co_u32_e32 v7, vcc, 0, v4, vcc
	flat_atomic_add v[6:7], v232 offset:1024
